# grid barrier between P2 and P3 removed: pooled-sample block published write-through + arrival counter; other P2->P3 deps are workgroup-local
# speedup vs baseline: 1.0732x; 1.0732x over previous
.LBB0_457:
	s_or_b64 exec, exec, s[36:37]
	v_lshlrev_b32_e64 v0, v12, 2
	v_cvt_f32_ubyte0_e32 v0, v0
	v_div_scale_f32 v6, s[12:13], v0, v0, v14
	v_rcp_f32_e32 v7, v6
	v_div_scale_f32 v8, vcc, v14, v0, v14
	v_add_u32_e32 v134, s71, v134
	v_fma_f32 v9, -v6, v7, 1.0
	v_fmac_f32_e32 v7, v9, v7
	v_mul_f32_e32 v9, v8, v7
	v_fma_f32 v10, -v6, v9, v8
	v_fmac_f32_e32 v9, v10, v7
	v_fma_f32 v6, -v6, v9, v8
	v_div_fmas_f32 v6, v6, v7, v9
	v_div_fixup_f32 v0, v6, v0, v14
	v_sub_f32_e32 v0, v0, v5
	v_bfe_u32 v5, v0, 16, 1
	v_add3_u32 v6, v0, v5, s0
	v_lshlrev_b32_e32 v0, 5, v12
	v_ashrrev_i32_e32 v5, 31, v4
	v_lshl_add_u64 v[4:5], v[0:1], 0, v[4:5]
	v_lshlrev_b64 v[4:5], 9, v[4:5]
	v_cmp_lt_i32_e32 vcc, s0, v134
	v_lshl_add_u64 v[4:5], v[2:3], 0, v[4:5]
	s_or_b64 s[18:19], vcc, s[18:19]
	global_store_short_d16_hi v[4:5], v6, off sc1
	s_andn2_b64 exec, exec, s[18:19]
	s_cbranch_execz .LBB0_498

.LBB0_498:
	s_or_b64 exec, exec, s[10:11]
	s_and_b64 vcc, exec, s[4:5]
	s_cbranch_vccz .LBB0_500
	s_ashr_i32 s0, s33, 6
	s_ashr_i32 s1, s0, 31
	s_lshl_b64 s[0:1], s[0:1], 17
	s_add_u32 s0, s68, s0
	v_lshlrev_b32_e32 v2, 3, v133
	v_lshlrev_b32_e32 v0, 4, v133
	s_addc_u32 s1, s69, s1
	v_and_b32_e32 v0, 0x1f0, v0
	v_mov_b32_e32 v1, 0
	v_and_b32_e32 v62, 0xffffff00, v2
	v_lshl_add_u64 v[60:61], s[0:1], 0, v[0:1]
	v_ashrrev_i32_e32 v63, 31, v62
	v_lshl_add_u64 v[0:1], v[62:63], 1, v[60:61]
	s_waitcnt vmcnt(0)
	s_barrier
	s_cmp_lg_u32 s81, 0
	s_cbranch_scc1 .Lp2_noarrive
	s_mov_b64 s[10:11], exec
	s_mov_b64 exec, 1
	v_mov_b32_e32 v252, 0x3000
	v_mov_b32_e32 v253, 1
	global_atomic_add v252, v253, s[92:93]
	s_mov_b64 exec, s[10:11]
.Lp2_noarrive:
	global_load_dwordx4 v[0:3], v[0:1], off
	v_add_u32_e32 v4, 0x1000, v62
	v_ashrrev_i32_e32 v5, 31, v4
	v_lshl_add_u64 v[4:5], v[4:5], 1, v[60:61]
	global_load_dwordx4 v[4:7], v[4:5], off
	v_add_u32_e32 v8, 0x2000, v62
	v_ashrrev_i32_e32 v9, 31, v8
	v_lshl_add_u64 v[8:9], v[8:9], 1, v[60:61]
	global_load_dwordx4 v[8:11], v[8:9], off
	v_add_u32_e32 v12, 0x3000, v62
	v_ashrrev_i32_e32 v13, 31, v12
	v_lshl_add_u64 v[12:13], v[12:13], 1, v[60:61]
	global_load_dwordx4 v[12:15], v[12:13], off
	v_add_u32_e32 v16, 0x4000, v62
	v_ashrrev_i32_e32 v17, 31, v16
	v_lshl_add_u64 v[16:17], v[16:17], 1, v[60:61]
	global_load_dwordx4 v[16:19], v[16:17], off
	v_add_u32_e32 v20, 0x5000, v62
	v_ashrrev_i32_e32 v21, 31, v20
	v_lshl_add_u64 v[20:21], v[20:21], 1, v[60:61]
	global_load_dwordx4 v[20:23], v[20:21], off
	v_add_u32_e32 v24, 0x6000, v62
	v_ashrrev_i32_e32 v25, 31, v24
	v_lshl_add_u64 v[24:25], v[24:25], 1, v[60:61]
	global_load_dwordx4 v[24:27], v[24:25], off
	v_add_u32_e32 v28, 0x7000, v62
	v_ashrrev_i32_e32 v29, 31, v28
	v_lshl_add_u64 v[28:29], v[28:29], 1, v[60:61]
	global_load_dwordx4 v[28:31], v[28:29], off
	v_add_u32_e32 v32, 0x8000, v62
	v_ashrrev_i32_e32 v33, 31, v32
	v_lshl_add_u64 v[32:33], v[32:33], 1, v[60:61]
	global_load_dwordx4 v[32:35], v[32:33], off
	v_add_u32_e32 v36, 0x9000, v62
	v_ashrrev_i32_e32 v37, 31, v36
	v_lshl_add_u64 v[36:37], v[36:37], 1, v[60:61]
	global_load_dwordx4 v[36:39], v[36:37], off
	v_add_u32_e32 v40, 0xa000, v62
	v_ashrrev_i32_e32 v41, 31, v40
	v_lshl_add_u64 v[40:41], v[40:41], 1, v[60:61]
	global_load_dwordx4 v[40:43], v[40:41], off
	v_add_u32_e32 v44, 0xb000, v62
	v_ashrrev_i32_e32 v45, 31, v44
	v_lshl_add_u64 v[44:45], v[44:45], 1, v[60:61]
	global_load_dwordx4 v[44:47], v[44:45], off
	v_add_u32_e32 v48, 0xc000, v62
	v_ashrrev_i32_e32 v49, 31, v48
	v_lshl_add_u64 v[48:49], v[48:49], 1, v[60:61]
	global_load_dwordx4 v[48:51], v[48:49], off
	v_add_u32_e32 v52, 0xd000, v62
	v_ashrrev_i32_e32 v53, 31, v52
	v_lshl_add_u64 v[52:53], v[52:53], 1, v[60:61]
	global_load_dwordx4 v[52:55], v[52:53], off
	v_add_u32_e32 v56, 0xe000, v62
	v_ashrrev_i32_e32 v57, 31, v56
	v_lshl_add_u64 v[56:57], v[56:57], 1, v[60:61]
	global_load_dwordx4 v[56:59], v[56:57], off
	v_add_u32_e32 v62, 0xf000, v62
	v_ashrrev_i32_e32 v63, 31, v62
	v_lshl_add_u64 v[60:61], v[62:63], 1, v[60:61]
	global_load_dwordx4 v[60:63], v[60:61], off
	v_and_b32_e32 v64, 0x1f0, v132
	v_add_u32_e32 v64, 0, v64
	v_ashrrev_i32_e32 v65, 5, v133
	s_movk_i32 s10, 0x210
	v_mad_u64_u32 v[66:67], s[0:1], v65, s10, v[64:65]
	s_waitcnt vmcnt(15)
	ds_write_b128 v66, v[0:3]
	v_add_u32_e32 v0, 0x200, v133
	v_ashrrev_i32_e32 v0, 5, v0
	v_mad_u64_u32 v[0:1], s[0:1], v0, s10, v[64:65]
	s_waitcnt vmcnt(14)
	ds_write_b128 v0, v[4:7]
	v_add_u32_e32 v0, 0x400, v133
	v_ashrrev_i32_e32 v0, 5, v0
	v_mad_u64_u32 v[0:1], s[0:1], v0, s10, v[64:65]
	s_waitcnt vmcnt(13)
	ds_write_b128 v0, v[8:11]
	v_add_u32_e32 v0, 0x600, v133
	v_ashrrev_i32_e32 v0, 5, v0
	v_mad_u64_u32 v[0:1], s[0:1], v0, s10, v[64:65]
	s_waitcnt vmcnt(12)
	ds_write_b128 v0, v[12:15]
	v_add_u32_e32 v0, 0x800, v133
	v_ashrrev_i32_e32 v0, 5, v0
	v_mad_u64_u32 v[0:1], s[0:1], v0, s10, v[64:65]
	s_waitcnt vmcnt(11)
	ds_write_b128 v0, v[16:19]
	v_add_u32_e32 v0, 0xa00, v133
	v_ashrrev_i32_e32 v0, 5, v0
	v_mad_u64_u32 v[0:1], s[0:1], v0, s10, v[64:65]
	s_waitcnt vmcnt(10)
	ds_write_b128 v0, v[20:23]
	v_add_u32_e32 v0, 0xc00, v133
	v_ashrrev_i32_e32 v0, 5, v0
	v_mad_u64_u32 v[0:1], s[0:1], v0, s10, v[64:65]
	s_waitcnt vmcnt(9)
	ds_write_b128 v0, v[24:27]
	v_add_u32_e32 v0, 0xe00, v133
	v_ashrrev_i32_e32 v0, 5, v0
	v_mad_u64_u32 v[0:1], s[0:1], v0, s10, v[64:65]
	s_waitcnt vmcnt(8)
	ds_write_b128 v0, v[28:31]
	v_add_u32_e32 v0, 0x1000, v133
	v_ashrrev_i32_e32 v0, 5, v0
	v_mad_u64_u32 v[0:1], s[0:1], v0, s10, v[64:65]
	s_waitcnt vmcnt(7)
	ds_write_b128 v0, v[32:35]
	v_add_u32_e32 v0, 0x1200, v133
	v_ashrrev_i32_e32 v0, 5, v0
	v_mad_u64_u32 v[0:1], s[0:1], v0, s10, v[64:65]
	s_waitcnt vmcnt(6)
	ds_write_b128 v0, v[36:39]
	v_add_u32_e32 v0, 0x1400, v133
	v_ashrrev_i32_e32 v0, 5, v0
	v_mad_u64_u32 v[0:1], s[0:1], v0, s10, v[64:65]
	s_waitcnt vmcnt(5)
	ds_write_b128 v0, v[40:43]
	v_add_u32_e32 v0, 0x1600, v133
	v_ashrrev_i32_e32 v0, 5, v0
	v_mad_u64_u32 v[0:1], s[0:1], v0, s10, v[64:65]
	s_waitcnt vmcnt(4)
	ds_write_b128 v0, v[44:47]
	v_add_u32_e32 v0, 0x1800, v133
	v_ashrrev_i32_e32 v0, 5, v0
	v_mad_u64_u32 v[0:1], s[0:1], v0, s10, v[64:65]
	s_waitcnt vmcnt(3)
	ds_write_b128 v0, v[48:51]
	v_add_u32_e32 v0, 0x1a00, v133
	v_ashrrev_i32_e32 v0, 5, v0
	v_mad_u64_u32 v[0:1], s[0:1], v0, s10, v[64:65]
	s_waitcnt vmcnt(2)
	ds_write_b128 v0, v[52:55]
	v_add_u32_e32 v0, 0x1c00, v133
	v_ashrrev_i32_e32 v0, 5, v0
	v_mad_u64_u32 v[0:1], s[0:1], v0, s10, v[64:65]
	s_waitcnt vmcnt(1)
	ds_write_b128 v0, v[56:59]
	v_add_u32_e32 v0, 0x1e00, v133
	v_ashrrev_i32_e32 v0, 5, v0
	v_mad_u64_u32 v[0:1], s[0:1], v0, s10, v[64:65]
	s_waitcnt vmcnt(0)
	ds_write_b128 v0, v[60:63]
.LBB0_500:
	s_waitcnt vmcnt(0)
	s_waitcnt lgkmcnt(0)
	s_barrier
	s_mov_b64 s[10:11], exec
	v_readlane_b32 s0, v239, 0
	v_readlane_b32 s1, v239, 1
	s_and_b64 s[0:1], s[10:11], s[0:1]
	s_mov_b64 exec, s[0:1]
	s_branch .LBB0_552

.LBB0_558:
	ds_read_b128 v[162:165], v64
	ds_read_b128 v[170:173], v64 offset:64
	v_add_u32_e32 v103, s1, v104
	v_subrev_u32_e32 v166, 64, v103
	s_cmpk_lg_i32 s10, 0x180
	s_cselect_b32 s12, s1, 0xc0
	v_add_u32_e32 v32, s12, v104
	v_add_u32_e32 v36, s12, v108
	v_add_u32_e32 v40, s12, v110
	s_waitcnt vmcnt(15) lgkmcnt(1)
	v_mfma_f32_16x16x32_bf16 v[162:165], v[162:165], v[0:3], 0
	v_add_u32_e32 v44, s12, v112
	v_ashrrev_i32_e32 v33, 31, v32
	v_ashrrev_i32_e32 v37, 31, v36
	s_waitcnt vmcnt(14) lgkmcnt(0)
	v_mfma_f32_16x16x32_bf16 v[162:165], v[170:173], v[4:7], v[162:165]
	ds_read_b128 v[170:173], v64 offset:128
	v_ashrrev_i32_e32 v41, 31, v40
	v_ashrrev_i32_e32 v45, 31, v44
	v_ashrrev_i32_e32 v167, 31, v166
	v_lshl_add_u64 v[34:35], v[32:33], 1, v[106:107]
	v_lshl_add_u64 v[32:33], v[32:33], 2, s[60:61]
	v_lshl_add_u64 v[38:39], v[36:37], 1, v[106:107]
	v_lshl_add_u64 v[36:37], v[36:37], 2, s[60:61]
	s_waitcnt vmcnt(13) lgkmcnt(0)
	v_mfma_f32_16x16x32_bf16 v[162:165], v[170:173], v[8:11], v[162:165]
	ds_read_b128 v[170:173], v64 offset:192
	v_lshl_add_u64 v[42:43], v[40:41], 1, v[106:107]
	v_lshl_add_u64 v[40:41], v[40:41], 2, s[60:61]
	v_lshl_add_u64 v[46:47], v[44:45], 1, v[106:107]
	v_lshl_add_u64 v[44:45], v[44:45], 2, s[60:61]
	global_load_dwordx2 v[118:119], v[34:35], off
	global_load_dwordx2 v[120:121], v[38:39], off
	s_waitcnt vmcnt(14) lgkmcnt(0)
	v_mfma_f32_16x16x32_bf16 v[162:165], v[170:173], v[12:15], v[162:165]
	ds_read_b128 v[170:173], v64 offset:256
	global_load_dwordx4 v[32:35], v[32:33], off
	s_mov_b32 s12, 0xa800000
	global_load_dwordx4 v[36:39], v[36:37], off
	s_waitcnt vmcnt(15) lgkmcnt(0)
	v_mfma_f32_16x16x32_bf16 v[162:165], v[170:173], v[16:19], v[162:165]
	ds_read_b128 v[170:173], v64 offset:320
	global_load_dwordx2 v[122:123], v[42:43], off
	global_load_dwordx2 v[124:125], v[46:47], off
	s_waitcnt vmcnt(16) lgkmcnt(0)
	v_mfma_f32_16x16x32_bf16 v[162:165], v[170:173], v[20:23], v[162:165]
	ds_read_b128 v[170:173], v64 offset:384
	global_load_dwordx4 v[40:43], v[40:41], off
	s_nop 0
	global_load_dwordx4 v[44:47], v[44:45], off
	s_waitcnt vmcnt(17) lgkmcnt(0)
	v_mfma_f32_16x16x32_bf16 v[162:165], v[170:173], v[24:27], v[162:165]
	ds_read_b128 v[170:173], v64 offset:448
	s_waitcnt vmcnt(16) lgkmcnt(0)
	v_mfma_f32_16x16x32_bf16 v[162:165], v[170:173], v[28:31], v[162:165]
	s_waitcnt vmcnt(15)
	v_lshlrev_b32_e32 v170, 16, v132
	v_mul_f32_e32 v103, 0xbfb8aa3b, v170
	v_exp_f32_e32 v103, v103
	v_and_b32_e32 v171, 0xffff0000, v132
	s_waitcnt vmcnt(14)
	s_nop 1
	v_pk_mul_f32 v[60:61], v[60:61], v[162:163]
	v_lshlrev_b32_e32 v132, 16, v133
	v_add_f32_e32 v103, 1.0, v103
	v_rcp_f32_e32 v172, v103
	v_mul_f32_e32 v103, 0xbfb8aa3b, v171
	v_exp_f32_e32 v103, v103
	v_and_b32_e32 v133, 0xffff0000, v133
	v_pk_mul_f32 v[62:63], v[62:63], v[164:165]
	v_add_f32_e32 v103, 1.0, v103
	v_rcp_f32_e32 v173, v103
	s_nop 0
	v_pk_mul_f32 v[162:163], v[172:173], v[170:171]
	s_nop 0
	v_pk_mul_f32 v[60:61], v[162:163], v[60:61]
	s_nop 0
	v_cvt_pk_bf16_f32 v60, v60, v61
	v_mul_f32_e32 v61, 0xbfb8aa3b, v132
	v_exp_f32_e32 v61, v61
	s_nop 0
	v_add_f32_e32 v61, 1.0, v61
	v_rcp_f32_e32 v162, v61
	v_mul_f32_e32 v61, 0xbfb8aa3b, v133
	v_exp_f32_e32 v61, v61
	s_nop 0
	v_add_f32_e32 v61, 1.0, v61
	v_rcp_f32_e32 v163, v61
	s_nop 0
	v_pk_mul_f32 v[132:133], v[162:163], v[132:133]
	s_nop 0
	v_pk_mul_f32 v[62:63], v[132:133], v[62:63]
	ds_read_b128 v[162:165], v64 offset:8512
	v_cvt_pk_bf16_f32 v61, v62, v63
	v_lshl_add_u64 v[62:63], v[166:167], 1, v[114:115]
	global_store_dwordx2 v[62:63], v[60:61], off offset:2048
	ds_read_b128 v[60:63], v64 offset:8448
	s_waitcnt lgkmcnt(0)
	v_mfma_f32_16x16x32_bf16 v[60:63], v[60:63], v[0:3], 0
	s_waitcnt vmcnt(13)
	v_lshlrev_b32_e32 v132, 16, v130
	v_and_b32_e32 v133, 0xffff0000, v130
	v_mul_f32_e32 v103, 0xbfb8aa3b, v132
	v_mfma_f32_16x16x32_bf16 v[60:63], v[162:165], v[4:7], v[60:63]
	ds_read_b128 v[162:165], v64 offset:8576
	v_exp_f32_e32 v103, v103
	s_waitcnt lgkmcnt(0)
	v_mfma_f32_16x16x32_bf16 v[60:63], v[162:165], v[8:11], v[60:63]
	ds_read_b128 v[162:165], v64 offset:8640
	v_add_f32_e32 v103, 1.0, v103
	s_waitcnt lgkmcnt(0)
	v_mfma_f32_16x16x32_bf16 v[60:63], v[162:165], v[12:15], v[60:63]
	ds_read_b128 v[162:165], v64 offset:8704
	s_waitcnt lgkmcnt(0)
	v_mfma_f32_16x16x32_bf16 v[60:63], v[162:165], v[16:19], v[60:63]
	ds_read_b128 v[162:165], v64 offset:8768
	s_waitcnt lgkmcnt(0)
	v_mfma_f32_16x16x32_bf16 v[60:63], v[162:165], v[20:23], v[60:63]
	ds_read_b128 v[162:165], v64 offset:8832
	s_waitcnt lgkmcnt(0)
	v_mfma_f32_16x16x32_bf16 v[60:63], v[162:165], v[24:27], v[60:63]
	ds_read_b128 v[162:165], v64 offset:8896
	s_waitcnt lgkmcnt(0)
	v_mfma_f32_16x16x32_bf16 v[60:63], v[162:165], v[28:31], v[60:63]
	v_rcp_f32_e32 v162, v103
	s_nop 6
	v_pk_mul_f32 v[56:57], v[56:57], v[60:61]
	v_mul_f32_e32 v60, 0xbfb8aa3b, v133
	v_exp_f32_e32 v60, v60
	v_pk_mul_f32 v[58:59], v[58:59], v[62:63]
	s_waitcnt vmcnt(12)
	v_lshlrev_b32_e32 v62, 16, v128
	v_and_b32_e32 v63, 0xffff0000, v128
	v_add_f32_e32 v60, 1.0, v60
	v_rcp_f32_e32 v163, v60
	v_mul_f32_e32 v103, 0xbfb8aa3b, v62
	v_exp_f32_e32 v103, v103
	s_waitcnt vmcnt(4)
	v_mov_b32_e32 v128, v122
	v_pk_mul_f32 v[60:61], v[162:163], v[132:133]
	v_add_f32_e32 v103, 1.0, v103
	v_pk_mul_f32 v[56:57], v[60:61], v[56:57]
	s_nop 0
	v_cvt_pk_bf16_f32 v60, v56, v57
	v_lshlrev_b32_e32 v56, 16, v131
	v_mul_f32_e32 v61, 0xbfb8aa3b, v56
	v_exp_f32_e32 v61, v61
	v_and_b32_e32 v57, 0xffff0000, v131
	v_add_f32_e32 v61, 1.0, v61
	v_rcp_f32_e32 v130, v61
	v_mul_f32_e32 v61, 0xbfb8aa3b, v57
	v_exp_f32_e32 v61, v61
	s_nop 0
	v_add_f32_e32 v61, 1.0, v61
	v_rcp_f32_e32 v131, v61
	s_nop 0
	v_pk_mul_f32 v[56:57], v[130:131], v[56:57]
	s_nop 0
	v_pk_mul_f32 v[56:57], v[56:57], v[58:59]
	ds_read_b128 v[130:133], v64 offset:16960
	v_cvt_pk_bf16_f32 v61, v56, v57
	v_lshl_add_u64 v[56:57], v[116:117], 0, s[10:11]
	v_add_co_u32_e32 v56, vcc, s12, v56
	s_add_u32 s10, s10, 0x80
	s_nop 0
	v_addc_co_u32_e32 v57, vcc, 0, v57, vcc
	global_store_dwordx2 v[56:57], v[60:61], off offset:2080
	ds_read_b128 v[58:61], v64 offset:16896
	s_waitcnt lgkmcnt(0)
	v_mfma_f32_16x16x32_bf16 v[58:61], v[58:61], v[0:3], 0
	s_addc_u32 s11, s11, 0
	s_add_i32 s1, s1, 64
	s_cmpk_lg_i32 s10, 0x200
	v_mfma_f32_16x16x32_bf16 v[58:61], v[130:133], v[4:7], v[58:61]
	ds_read_b128 v[130:133], v64 offset:17024
	s_waitcnt lgkmcnt(0)
	v_mfma_f32_16x16x32_bf16 v[58:61], v[130:133], v[8:11], v[58:61]
	ds_read_b128 v[130:133], v64 offset:17088
	s_waitcnt lgkmcnt(0)
	v_mfma_f32_16x16x32_bf16 v[58:61], v[130:133], v[12:15], v[58:61]
	ds_read_b128 v[130:133], v64 offset:17152
	s_waitcnt lgkmcnt(0)
	v_mfma_f32_16x16x32_bf16 v[58:61], v[130:133], v[16:19], v[58:61]
	ds_read_b128 v[130:133], v64 offset:17216
	s_waitcnt lgkmcnt(0)
	v_mfma_f32_16x16x32_bf16 v[58:61], v[130:133], v[20:23], v[58:61]
	ds_read_b128 v[130:133], v64 offset:17280
	s_waitcnt lgkmcnt(0)
	v_mfma_f32_16x16x32_bf16 v[58:61], v[130:133], v[24:27], v[58:61]
	ds_read_b128 v[130:133], v64 offset:17344
	s_waitcnt lgkmcnt(0)
	v_mfma_f32_16x16x32_bf16 v[58:61], v[130:133], v[28:31], v[58:61]
	v_rcp_f32_e32 v130, v103
	v_mov_b32_e32 v132, v118
	v_mov_b32_e32 v133, v119
	s_nop 4
	v_pk_mul_f32 v[52:53], v[52:53], v[58:59]
	v_mul_f32_e32 v58, 0xbfb8aa3b, v63
	v_exp_f32_e32 v58, v58
	v_pk_mul_f32 v[54:55], v[54:55], v[60:61]
	v_add_f32_e32 v58, 1.0, v58
	v_rcp_f32_e32 v131, v58
	s_nop 0
	v_pk_mul_f32 v[58:59], v[130:131], v[62:63]
	s_nop 0
	v_pk_mul_f32 v[52:53], v[58:59], v[52:53]
	v_lshlrev_b32_e32 v58, 16, v129
	v_cvt_pk_bf16_f32 v52, v52, v53
	v_mul_f32_e32 v53, 0xbfb8aa3b, v58
	v_exp_f32_e32 v53, v53
	v_and_b32_e32 v59, 0xffff0000, v129
	v_mov_b32_e32 v130, v120
	v_mov_b32_e32 v131, v121
	v_add_f32_e32 v53, 1.0, v53
	v_rcp_f32_e32 v62, v53
	v_mul_f32_e32 v53, 0xbfb8aa3b, v59
	v_exp_f32_e32 v53, v53
	v_mov_b32_e32 v129, v123
	v_add_f32_e32 v53, 1.0, v53
	v_rcp_f32_e32 v63, v53
	s_nop 0
	v_pk_mul_f32 v[58:59], v[62:63], v[58:59]
	s_nop 0
	v_pk_mul_f32 v[54:55], v[58:59], v[54:55]
	ds_read_b128 v[58:61], v64 offset:25408
	v_cvt_pk_bf16_f32 v53, v54, v55
	global_store_dwordx2 v[56:57], v[52:53], off offset:2112
	ds_read_b128 v[52:55], v64 offset:25344
	s_waitcnt lgkmcnt(0)
	v_mfma_f32_16x16x32_bf16 v[52:55], v[52:55], v[0:3], 0
	v_mov_b32_e32 v62, v34
	v_mov_b32_e32 v63, v35
	v_mfma_f32_16x16x32_bf16 v[52:55], v[58:61], v[4:7], v[52:55]
	ds_read_b128 v[58:61], v64 offset:25472
	s_waitcnt lgkmcnt(0)
	v_mfma_f32_16x16x32_bf16 v[52:55], v[58:61], v[8:11], v[52:55]
	ds_read_b128 v[58:61], v64 offset:25536
	s_waitcnt lgkmcnt(0)
	v_mfma_f32_16x16x32_bf16 v[52:55], v[58:61], v[12:15], v[52:55]
	ds_read_b128 v[58:61], v64 offset:25600
	s_waitcnt lgkmcnt(0)
	v_mfma_f32_16x16x32_bf16 v[52:55], v[58:61], v[16:19], v[52:55]
	ds_read_b128 v[58:61], v64 offset:25664
	s_waitcnt lgkmcnt(0)
	v_mfma_f32_16x16x32_bf16 v[52:55], v[58:61], v[20:23], v[52:55]
	ds_read_b128 v[58:61], v64 offset:25728
	s_waitcnt lgkmcnt(0)
	v_mfma_f32_16x16x32_bf16 v[52:55], v[58:61], v[24:27], v[52:55]
	ds_read_b128 v[58:61], v64 offset:25792
	v_add_u32_e32 v64, 0x8400, v64
	s_waitcnt lgkmcnt(0)
	v_mfma_f32_16x16x32_bf16 v[52:55], v[58:61], v[28:31], v[52:55]
	v_lshlrev_b32_e32 v58, 16, v126
	v_and_b32_e32 v59, 0xffff0000, v126
	v_mul_f32_e32 v60, 0xbfb8aa3b, v58
	s_nop 4
	v_pk_mul_f32 v[48:49], v[48:49], v[52:53]
	v_mul_f32_e32 v52, 0xbfb8aa3b, v59
	v_exp_f32_e32 v60, v60
	v_exp_f32_e32 v52, v52
	v_pk_mul_f32 v[50:51], v[50:51], v[54:55]
	s_waitcnt vmcnt(5)
	v_mov_b32_e32 v126, v124
	v_add_f32_e32 v60, 1.0, v60
	v_add_f32_e32 v52, 1.0, v52
	v_rcp_f32_e32 v60, v60
	v_rcp_f32_e32 v61, v52
	s_waitcnt vmcnt(4)
	v_mov_b32_e32 v54, v42
	v_mov_b32_e32 v55, v43
	v_pk_mul_f32 v[52:53], v[60:61], v[58:59]
	s_nop 0
	v_pk_mul_f32 v[48:49], v[52:53], v[48:49]
	v_lshlrev_b32_e32 v52, 16, v127
	v_cvt_pk_bf16_f32 v48, v48, v49
	v_mul_f32_e32 v49, 0xbfb8aa3b, v52
	v_exp_f32_e32 v49, v49
	v_and_b32_e32 v53, 0xffff0000, v127
	v_mov_b32_e32 v127, v125
	v_mov_b32_e32 v60, v32
	v_add_f32_e32 v49, 1.0, v49
	v_rcp_f32_e32 v58, v49
	v_mul_f32_e32 v49, 0xbfb8aa3b, v53
	v_exp_f32_e32 v49, v49
	v_mov_b32_e32 v61, v33
	v_add_f32_e32 v49, 1.0, v49
	v_rcp_f32_e32 v59, v49
	s_nop 0
	v_pk_mul_f32 v[52:53], v[58:59], v[52:53]
	s_nop 0
	v_pk_mul_f32 v[50:51], v[52:53], v[50:51]
	v_mov_b32_e32 v58, v38
	v_cvt_pk_bf16_f32 v49, v50, v51
	global_store_dwordx2 v[56:57], v[48:49], off offset:2144
	v_mov_b32_e32 v56, v36
	v_mov_b32_e32 v57, v37
	v_mov_b32_e32 v59, v39
	v_mov_b32_e32 v52, v40
	v_mov_b32_e32 v53, v41
	s_waitcnt vmcnt(4)
	v_mov_b32_e32 v48, v44
	v_mov_b32_e32 v49, v45
	v_mov_b32_e32 v50, v46
	v_mov_b32_e32 v51, v47
	s_cbranch_scc1 .LBB0_558
	s_cmp_lg_u32 s0, 0
	s_cbranch_scc1 .LBB0_554
	v_mov_b32_e32 v252, 0x3000
	s_mov_b32 s13, 0
.Lp3_wait:
	global_load_dword v253, v252, s[92:93] sc1
	s_waitcnt vmcnt(0)
	v_readfirstlane_b32 s12, v253
	s_add_i32 s13, s13, 1
	s_cmpk_gt_u32 s12, 0xff
	s_cbranch_scc1 .Lp3_ready
	s_sleep 2
	s_cmp_lt_u32 s13, 0x100000
	s_cbranch_scc1 .Lp3_wait
.Lp3_ready:
	buffer_inv sc1
	s_waitcnt vmcnt(0)
	ds_read_b128 v[0:3], v160
	ds_read_b128 v[4:7], v160 offset:64
	ds_read_b128 v[8:11], v160 offset:128
	ds_read_b128 v[12:15], v160 offset:192
	ds_read_b128 v[16:19], v160 offset:256
	ds_read_b128 v[20:23], v160 offset:320
	ds_read_b128 v[24:27], v160 offset:384
	ds_read_b128 v[28:31], v160 offset:448
	ds_read_b128 v[32:35], v161
	ds_read_b128 v[36:39], v161 offset:64
	ds_read_b128 v[40:43], v161 offset:128
	ds_read_b128 v[44:47], v161 offset:192
	ds_read_b128 v[48:51], v161 offset:256
	ds_read_b128 v[52:55], v161 offset:320
	ds_read_b128 v[56:59], v161 offset:384
	ds_read_b128 v[60:63], v161 offset:448
	v_add_u32_e32 v110, v104, v141
	v_add_u32_e32 v112, v104, v142
	s_lshl_b64 s[0:1], s[8:9], 14
	v_ashrrev_i32_e32 v111, 31, v110
	v_ashrrev_i32_e32 v113, 31, v112
	v_lshl_add_u64 v[106:107], v[100:101], 0, s[0:1]
	v_lshl_add_u64 v[108:109], v[110:111], 2, s[60:61]
	v_lshl_add_u64 v[104:105], v[112:113], 2, s[60:61]
	s_mov_b32 s0, 0
	s_mov_b64 s[8:9], -1
	v_lshlrev_b64 v[110:111], 1, v[110:111]
	v_lshlrev_b64 v[112:113], 1, v[112:113]
